# K-fragment prefetch + permlane swap in attention; SwiGLU epilogue: ss loads hoisted with counted vmcnt, write-through (sc1) H stores
# speedup vs baseline: 1.0115x; 1.0094x over previous
; __device__ __forceinline__ float sigmoidf_(float x) { return __builtin_amdgcn_rcpf(1.f + __builtin_amdgcn_exp2f(-x * LOG2E)); }
; #define EPI_ROWS(...) _Pragma("unroll") for (int ai = 0; ai < 2; ++ai) _Pragma("unroll") for (int m = 0; m < 4; ++m) { const int row = row0 + ai * 128 + m * 16; __VA_ARGS__ __builtin_amdgcn_sched_barrier(0); }
; __device__ __forceinline__ u32x4 pack8(f32x4 a, f32x4 b) { u32x4 w; w.x = pk2(a[0], a[1]); w.y = pk2(a[2], a[3]); w.z = pk2(b[0], b[1]); w.w = pk2(b[2], b[3]); return w; }
;     __device__ __forceinline__ void operator()(AccRef acc, const Unit& u, int wr, int wc, int fr, int fq) const {
;         const int row0 = u.pm * 256 + wr * 64 + fr, col0 = u.pn * 128 + wc * 32 + 8 * fq;
;         EPI_ROWS(
;             const float rs = __builtin_amdgcn_rsqf(ss[row] * (1.f / 1024.f) + EPS);
;             f32x4 o[2];
;             _Pragma("unroll") for (int n = 0; n < 2; ++n) _Pragma("unroll") for (int i = 0; i < 4; ++i) { const float gg = acc[ai][0][m][n][i] * rs, uu = acc[ai][1][m][n][i] * rs; o[n][i] = gg * sigmoidf_(gg) * uu; }
;             *(u32x4*)(H + (size_t)row * DFF + col0) = pack8(o[0], o[1]);
;         )
;     }
.LBB0_207:
	v_lshl_add_u32 v138, s22, 8, v147
	v_ashrrev_i32_e32 v139, 31, v138
	v_lshl_add_u64 v[140:141], v[138:139], 2, s[6:7]
	global_load_dword v184, v[140:141], off
	global_load_dword v185, v[140:141], off offset:64
	global_load_dword v186, v[140:141], off offset:128
	global_load_dword v187, v[140:141], off offset:192
	global_load_dword v188, v[140:141], off offset:512
	global_load_dword v189, v[140:141], off offset:576
	global_load_dword v190, v[140:141], off offset:640
	global_load_dword v191, v[140:141], off offset:704
	v_lshl_or_b32 v136, s76, 7, v148
	v_mov_b64_e32 v[142:143], s[24:25]
	v_ashrrev_i32_e32 v137, 31, v136
	v_mad_i64_i32 v[158:159], s[26:27], v138, s75, v[142:143]
	v_lshlrev_b64 v[136:137], 1, v[136:137]
	s_waitcnt vmcnt(7)
	v_fmamk_f32 v139, v184, 0x3a800000, v154
	v_rsq_f32_e32 v156, v139
	s_nop 0
	v_pk_mul_f32 v[126:127], v[126:127], v[156:157] op_sel_hi:[1,0]
	v_pk_mul_f32 v[128:129], v[128:129], v[156:157] op_sel_hi:[1,0]
	v_pk_mul_f32 v[122:123], v[122:123], v[156:157] op_sel_hi:[1,0]
	v_pk_mul_f32 v[124:125], v[124:125], v[156:157] op_sel_hi:[1,0]
	v_pk_mul_f32 v[118:119], v[118:119], v[156:157] op_sel_hi:[1,0]
	v_pk_mul_f32 v[120:121], v[120:121], v[156:157] op_sel_hi:[1,0]
	v_pk_mul_f32 v[114:115], v[114:115], v[156:157] op_sel_hi:[1,0]
	v_pk_mul_f32 v[116:117], v[116:117], v[156:157] op_sel_hi:[1,0]
	v_mul_f32_e32 v139, 0xbfb8aa3b, v126
	v_mul_f32_e32 v155, 0xbfb8aa3b, v127
	v_mul_f32_e32 v156, 0xbfb8aa3b, v128
	v_mul_f32_e32 v157, 0xbfb8aa3b, v129
	v_mul_f32_e32 v160, 0xbfb8aa3b, v122
	v_mul_f32_e32 v161, 0xbfb8aa3b, v123
	v_mul_f32_e32 v162, 0xbfb8aa3b, v124
	v_mul_f32_e32 v163, 0xbfb8aa3b, v125
	v_exp_f32_e32 v139, v139
	v_exp_f32_e32 v155, v155
	v_exp_f32_e32 v156, v156
	v_exp_f32_e32 v157, v157
	v_exp_f32_e32 v160, v160
	v_exp_f32_e32 v161, v161
	v_exp_f32_e32 v162, v162
	v_exp_f32_e32 v163, v163
	v_add_f32_e32 v139, 1.0, v139
	v_add_f32_e32 v155, 1.0, v155
	v_add_f32_e32 v164, 1.0, v156
	v_add_f32_e32 v165, 1.0, v157
	v_add_f32_e32 v166, 1.0, v160
	v_add_f32_e32 v167, 1.0, v161
	v_add_f32_e32 v168, 1.0, v162
	v_add_f32_e32 v169, 1.0, v163
	v_rcp_f32_e32 v156, v139
	v_rcp_f32_e32 v157, v155
	v_rcp_f32_e32 v160, v164
	v_rcp_f32_e32 v161, v165
	v_rcp_f32_e32 v162, v166
	v_rcp_f32_e32 v163, v167
	v_rcp_f32_e32 v164, v168
	v_rcp_f32_e32 v165, v169
	v_pk_mul_f32 v[126:127], v[126:127], v[156:157]
	v_pk_mul_f32 v[128:129], v[128:129], v[160:161]
	v_pk_mul_f32 v[122:123], v[122:123], v[162:163]
	v_pk_mul_f32 v[124:125], v[124:125], v[164:165]
	v_pk_mul_f32 v[118:119], v[118:119], v[126:127]
	v_pk_mul_f32 v[120:121], v[120:121], v[128:129]
	v_pk_mul_f32 v[122:123], v[114:115], v[122:123]
	v_pk_mul_f32 v[124:125], v[116:117], v[124:125]
	v_cvt_pk_bf16_f32 v114, v118, v119
	v_cvt_pk_bf16_f32 v115, v120, v121
	v_cvt_pk_bf16_f32 v116, v122, v123
	v_cvt_pk_bf16_f32 v117, v124, v125
	v_lshl_add_u64 v[118:119], v[158:159], 0, v[136:137]
	global_store_dwordx4 v[118:119], v[114:117], off sc1
	s_nop 1
	v_or_b32_e32 v114, 16, v138
	v_ashrrev_i32_e32 v115, 31, v114
	v_lshl_add_u64 v[116:117], v[114:115], 2, s[6:7]
	s_nop 0
	s_waitcnt vmcnt(7)
	v_fmamk_f32 v115, v185, 0x3a800000, v154
	v_rsq_f32_e32 v116, v115
	v_mad_i64_i32 v[114:115], s[26:27], v114, s75, v[142:143]
	v_pk_mul_f32 v[110:111], v[110:111], v[116:117] op_sel_hi:[1,0]
	v_pk_mul_f32 v[112:113], v[112:113], v[116:117] op_sel_hi:[1,0]
	v_pk_mul_f32 v[106:107], v[106:107], v[116:117] op_sel_hi:[1,0]
	v_pk_mul_f32 v[108:109], v[108:109], v[116:117] op_sel_hi:[1,0]
	v_pk_mul_f32 v[102:103], v[102:103], v[116:117] op_sel_hi:[1,0]
	v_pk_mul_f32 v[104:105], v[104:105], v[116:117] op_sel_hi:[1,0]
	v_pk_mul_f32 v[98:99], v[98:99], v[116:117] op_sel_hi:[1,0]
	v_pk_mul_f32 v[100:101], v[100:101], v[116:117] op_sel_hi:[1,0]
	v_mul_f32_e32 v116, 0xbfb8aa3b, v110
	v_mul_f32_e32 v117, 0xbfb8aa3b, v111
	v_mul_f32_e32 v118, 0xbfb8aa3b, v112
	v_mul_f32_e32 v119, 0xbfb8aa3b, v113
	v_mul_f32_e32 v120, 0xbfb8aa3b, v106
	v_mul_f32_e32 v121, 0xbfb8aa3b, v107
	v_mul_f32_e32 v122, 0xbfb8aa3b, v108
	v_mul_f32_e32 v123, 0xbfb8aa3b, v109
	v_exp_f32_e32 v116, v116
	v_exp_f32_e32 v117, v117
	v_exp_f32_e32 v118, v118
	v_exp_f32_e32 v119, v119
	v_exp_f32_e32 v120, v120
	v_exp_f32_e32 v121, v121
	v_exp_f32_e32 v122, v122
	v_exp_f32_e32 v123, v123
	v_add_f32_e32 v116, 1.0, v116
	v_add_f32_e32 v117, 1.0, v117
	v_add_f32_e32 v118, 1.0, v118
	v_add_f32_e32 v119, 1.0, v119
	v_add_f32_e32 v120, 1.0, v120
	v_add_f32_e32 v121, 1.0, v121
	v_add_f32_e32 v122, 1.0, v122
	v_add_f32_e32 v123, 1.0, v123
	v_rcp_f32_e32 v116, v116
	v_rcp_f32_e32 v117, v117
	v_rcp_f32_e32 v118, v118
	v_rcp_f32_e32 v119, v119
	v_rcp_f32_e32 v120, v120
	v_rcp_f32_e32 v121, v121
	v_rcp_f32_e32 v122, v122
	v_rcp_f32_e32 v123, v123
	v_pk_mul_f32 v[110:111], v[110:111], v[116:117]
	v_pk_mul_f32 v[112:113], v[112:113], v[118:119]
	v_pk_mul_f32 v[106:107], v[106:107], v[120:121]
	v_pk_mul_f32 v[108:109], v[108:109], v[122:123]
	v_pk_mul_f32 v[102:103], v[102:103], v[110:111]
	v_pk_mul_f32 v[104:105], v[104:105], v[112:113]
	v_pk_mul_f32 v[106:107], v[98:99], v[106:107]
	v_pk_mul_f32 v[108:109], v[100:101], v[108:109]
	v_cvt_pk_bf16_f32 v98, v102, v103
	v_cvt_pk_bf16_f32 v99, v104, v105
	v_cvt_pk_bf16_f32 v100, v106, v107
	v_cvt_pk_bf16_f32 v101, v108, v109
	v_lshl_add_u64 v[102:103], v[114:115], 0, v[136:137]
	global_store_dwordx4 v[102:103], v[98:101], off sc1
	s_nop 1
	v_or_b32_e32 v98, 32, v138
	v_ashrrev_i32_e32 v99, 31, v98
	v_lshl_add_u64 v[100:101], v[98:99], 2, s[6:7]
	s_nop 0
	s_waitcnt vmcnt(7)
; __device__ __forceinline__ float sigmoidf_(float x) { return __builtin_amdgcn_rcpf(1.f + __builtin_amdgcn_exp2f(-x * LOG2E)); }
; #define EPI_ROWS(...) _Pragma("unroll") for (int ai = 0; ai < 2; ++ai) _Pragma("unroll") for (int m = 0; m < 4; ++m) { const int row = row0 + ai * 128 + m * 16; __VA_ARGS__ __builtin_amdgcn_sched_barrier(0); }
; __device__ __forceinline__ u32x4 pack8(f32x4 a, f32x4 b) { u32x4 w; w.x = pk2(a[0], a[1]); w.y = pk2(a[2], a[3]); w.z = pk2(b[0], b[1]); w.w = pk2(b[2], b[3]); return w; }
;     __device__ __forceinline__ void operator()(AccRef acc, const Unit& u, int wr, int wc, int fr, int fq) const {
;         const int row0 = u.pm * 256 + wr * 64 + fr, col0 = u.pn * 128 + wc * 32 + 8 * fq;
;         EPI_ROWS(
;             const float rs = __builtin_amdgcn_rsqf(ss[row] * (1.f / 1024.f) + EPS);
;             f32x4 o[2];
;             _Pragma("unroll") for (int n = 0; n < 2; ++n) _Pragma("unroll") for (int i = 0; i < 4; ++i) { const float gg = acc[ai][0][m][n][i] * rs, uu = acc[ai][1][m][n][i] * rs; o[n][i] = gg * sigmoidf_(gg) * uu; }
;             *(u32x4*)(H + (size_t)row * DFF + col0) = pack8(o[0], o[1]);
;         )
;     }
	v_fmamk_f32 v99, v186, 0x3a800000, v154
	v_rsq_f32_e32 v100, v99
	v_mad_i64_i32 v[98:99], s[26:27], v98, s75, v[142:143]
	v_pk_mul_f32 v[94:95], v[94:95], v[100:101] op_sel_hi:[1,0]
	v_pk_mul_f32 v[96:97], v[96:97], v[100:101] op_sel_hi:[1,0]
	v_pk_mul_f32 v[90:91], v[90:91], v[100:101] op_sel_hi:[1,0]
	v_pk_mul_f32 v[92:93], v[92:93], v[100:101] op_sel_hi:[1,0]
	v_pk_mul_f32 v[86:87], v[86:87], v[100:101] op_sel_hi:[1,0]
	v_pk_mul_f32 v[88:89], v[88:89], v[100:101] op_sel_hi:[1,0]
	v_pk_mul_f32 v[82:83], v[82:83], v[100:101] op_sel_hi:[1,0]
	v_pk_mul_f32 v[84:85], v[84:85], v[100:101] op_sel_hi:[1,0]
	v_mul_f32_e32 v100, 0xbfb8aa3b, v94
	v_mul_f32_e32 v101, 0xbfb8aa3b, v95
	v_mul_f32_e32 v102, 0xbfb8aa3b, v96
	v_mul_f32_e32 v103, 0xbfb8aa3b, v97
	v_mul_f32_e32 v104, 0xbfb8aa3b, v90
	v_mul_f32_e32 v105, 0xbfb8aa3b, v91
	v_mul_f32_e32 v106, 0xbfb8aa3b, v92
	v_mul_f32_e32 v107, 0xbfb8aa3b, v93
	v_exp_f32_e32 v100, v100
	v_exp_f32_e32 v101, v101
	v_exp_f32_e32 v102, v102
	v_exp_f32_e32 v103, v103
	v_exp_f32_e32 v104, v104
	v_exp_f32_e32 v105, v105
	v_exp_f32_e32 v106, v106
	v_exp_f32_e32 v107, v107
	v_add_f32_e32 v100, 1.0, v100
	v_add_f32_e32 v101, 1.0, v101
	v_add_f32_e32 v102, 1.0, v102
	v_add_f32_e32 v103, 1.0, v103
	v_add_f32_e32 v104, 1.0, v104
	v_add_f32_e32 v105, 1.0, v105
	v_add_f32_e32 v106, 1.0, v106
	v_add_f32_e32 v107, 1.0, v107
	v_rcp_f32_e32 v100, v100
	v_rcp_f32_e32 v101, v101
	v_rcp_f32_e32 v102, v102
	v_rcp_f32_e32 v103, v103
	v_rcp_f32_e32 v104, v104
	v_rcp_f32_e32 v105, v105
	v_rcp_f32_e32 v106, v106
	v_rcp_f32_e32 v107, v107
	v_pk_mul_f32 v[94:95], v[94:95], v[100:101]
	v_pk_mul_f32 v[96:97], v[96:97], v[102:103]
	v_pk_mul_f32 v[90:91], v[90:91], v[104:105]
	v_pk_mul_f32 v[92:93], v[92:93], v[106:107]
	v_pk_mul_f32 v[86:87], v[86:87], v[94:95]
	v_pk_mul_f32 v[88:89], v[88:89], v[96:97]
	v_pk_mul_f32 v[90:91], v[82:83], v[90:91]
	v_pk_mul_f32 v[92:93], v[84:85], v[92:93]
	v_cvt_pk_bf16_f32 v82, v86, v87
	v_cvt_pk_bf16_f32 v83, v88, v89
	v_cvt_pk_bf16_f32 v84, v90, v91
	v_cvt_pk_bf16_f32 v85, v92, v93
	v_lshl_add_u64 v[86:87], v[98:99], 0, v[136:137]
	global_store_dwordx4 v[86:87], v[82:85], off sc1
	s_nop 1
	v_or_b32_e32 v82, 48, v138
	v_ashrrev_i32_e32 v83, 31, v82
	v_lshl_add_u64 v[84:85], v[82:83], 2, s[6:7]
	s_nop 0
	s_waitcnt vmcnt(7)
	v_fmamk_f32 v83, v187, 0x3a800000, v154
	v_rsq_f32_e32 v84, v83
	v_mad_i64_i32 v[82:83], s[26:27], v82, s75, v[142:143]
	v_pk_mul_f32 v[78:79], v[78:79], v[84:85] op_sel_hi:[1,0]
	v_pk_mul_f32 v[80:81], v[80:81], v[84:85] op_sel_hi:[1,0]
	v_pk_mul_f32 v[74:75], v[74:75], v[84:85] op_sel_hi:[1,0]
	v_pk_mul_f32 v[76:77], v[76:77], v[84:85] op_sel_hi:[1,0]
	v_pk_mul_f32 v[70:71], v[70:71], v[84:85] op_sel_hi:[1,0]
	v_pk_mul_f32 v[72:73], v[72:73], v[84:85] op_sel_hi:[1,0]
	v_pk_mul_f32 v[66:67], v[66:67], v[84:85] op_sel_hi:[1,0]
	v_pk_mul_f32 v[68:69], v[68:69], v[84:85] op_sel_hi:[1,0]
	v_mul_f32_e32 v84, 0xbfb8aa3b, v78
	v_mul_f32_e32 v85, 0xbfb8aa3b, v79
	v_mul_f32_e32 v86, 0xbfb8aa3b, v80
	v_mul_f32_e32 v87, 0xbfb8aa3b, v81
	v_mul_f32_e32 v88, 0xbfb8aa3b, v74
	v_mul_f32_e32 v89, 0xbfb8aa3b, v75
	v_mul_f32_e32 v90, 0xbfb8aa3b, v76
	v_mul_f32_e32 v91, 0xbfb8aa3b, v77
	v_exp_f32_e32 v84, v84
	v_exp_f32_e32 v85, v85
	v_exp_f32_e32 v86, v86
	v_exp_f32_e32 v87, v87
	v_exp_f32_e32 v88, v88
	v_exp_f32_e32 v89, v89
	v_exp_f32_e32 v90, v90
	v_exp_f32_e32 v91, v91
	v_add_f32_e32 v84, 1.0, v84
	v_add_f32_e32 v85, 1.0, v85
	v_add_f32_e32 v86, 1.0, v86
	v_add_f32_e32 v87, 1.0, v87
	v_add_f32_e32 v88, 1.0, v88
	v_add_f32_e32 v89, 1.0, v89
	v_add_f32_e32 v90, 1.0, v90
	v_add_f32_e32 v91, 1.0, v91
	v_rcp_f32_e32 v84, v84
	v_rcp_f32_e32 v85, v85
	v_rcp_f32_e32 v86, v86
	v_rcp_f32_e32 v87, v87
	v_rcp_f32_e32 v88, v88
	v_rcp_f32_e32 v89, v89
	v_rcp_f32_e32 v90, v90
	v_rcp_f32_e32 v91, v91
	v_pk_mul_f32 v[78:79], v[78:79], v[84:85]
	v_pk_mul_f32 v[80:81], v[80:81], v[86:87]
	v_pk_mul_f32 v[74:75], v[74:75], v[88:89]
	v_pk_mul_f32 v[76:77], v[76:77], v[90:91]
	v_pk_mul_f32 v[70:71], v[70:71], v[78:79]
	v_pk_mul_f32 v[72:73], v[72:73], v[80:81]
	v_pk_mul_f32 v[74:75], v[66:67], v[74:75]
	v_pk_mul_f32 v[76:77], v[68:69], v[76:77]
	v_cvt_pk_bf16_f32 v66, v70, v71
	v_cvt_pk_bf16_f32 v67, v72, v73
	v_cvt_pk_bf16_f32 v68, v74, v75
	v_cvt_pk_bf16_f32 v69, v76, v77
	v_lshl_add_u64 v[70:71], v[82:83], 0, v[136:137]
	global_store_dwordx4 v[70:71], v[66:69], off sc1
	s_nop 0
	s_nop 0
	v_add_u32_e32 v67, 0x80, v138
	v_mad_i64_i32 v[68:69], s[26:27], v67, s75, v[142:143]
	s_waitcnt vmcnt(7)
	v_fmamk_f32 v66, v188, 0x3a800000, v154
	v_rsq_f32_e32 v66, v66
	s_nop 0
	v_pk_mul_f32 v[62:63], v[62:63], v[66:67] op_sel_hi:[1,0]
	v_pk_mul_f32 v[64:65], v[64:65], v[66:67] op_sel_hi:[1,0]
	v_pk_mul_f32 v[58:59], v[58:59], v[66:67] op_sel_hi:[1,0]
	v_pk_mul_f32 v[60:61], v[60:61], v[66:67] op_sel_hi:[1,0]
	v_pk_mul_f32 v[54:55], v[54:55], v[66:67] op_sel_hi:[1,0]
	v_pk_mul_f32 v[56:57], v[56:57], v[66:67] op_sel_hi:[1,0]
	v_pk_mul_f32 v[50:51], v[50:51], v[66:67] op_sel_hi:[1,0]
	v_pk_mul_f32 v[52:53], v[52:53], v[66:67] op_sel_hi:[1,0]
	v_mul_f32_e32 v66, 0xbfb8aa3b, v62
	v_mul_f32_e32 v67, 0xbfb8aa3b, v63
	v_mul_f32_e32 v70, 0xbfb8aa3b, v64
	v_mul_f32_e32 v71, 0xbfb8aa3b, v65
	v_mul_f32_e32 v72, 0xbfb8aa3b, v58
	v_mul_f32_e32 v73, 0xbfb8aa3b, v59
	v_mul_f32_e32 v74, 0xbfb8aa3b, v60
	v_mul_f32_e32 v75, 0xbfb8aa3b, v61
	v_exp_f32_e32 v66, v66
	v_exp_f32_e32 v67, v67
	v_exp_f32_e32 v70, v70
	v_exp_f32_e32 v71, v71
	v_exp_f32_e32 v72, v72
	v_exp_f32_e32 v73, v73
	v_exp_f32_e32 v74, v74
	v_exp_f32_e32 v75, v75
	v_add_f32_e32 v66, 1.0, v66
	v_add_f32_e32 v67, 1.0, v67
	v_add_f32_e32 v70, 1.0, v70
	v_add_f32_e32 v71, 1.0, v71
	v_add_f32_e32 v72, 1.0, v72
	v_add_f32_e32 v73, 1.0, v73
	v_add_f32_e32 v74, 1.0, v74
	v_add_f32_e32 v75, 1.0, v75
	v_rcp_f32_e32 v66, v66
	v_rcp_f32_e32 v67, v67
	v_rcp_f32_e32 v70, v70
	v_rcp_f32_e32 v71, v71
	v_rcp_f32_e32 v72, v72
	v_rcp_f32_e32 v73, v73
	v_rcp_f32_e32 v74, v74
	v_rcp_f32_e32 v75, v75
	v_pk_mul_f32 v[62:63], v[62:63], v[66:67]
	v_pk_mul_f32 v[64:65], v[64:65], v[70:71]
	v_pk_mul_f32 v[58:59], v[58:59], v[72:73]
	v_pk_mul_f32 v[60:61], v[60:61], v[74:75]
	v_pk_mul_f32 v[54:55], v[54:55], v[62:63]
	v_pk_mul_f32 v[56:57], v[56:57], v[64:65]
	v_pk_mul_f32 v[58:59], v[50:51], v[58:59]
	v_pk_mul_f32 v[60:61], v[52:53], v[60:61]
	v_cvt_pk_bf16_f32 v50, v54, v55
	v_cvt_pk_bf16_f32 v51, v56, v57
	v_cvt_pk_bf16_f32 v52, v58, v59
	v_cvt_pk_bf16_f32 v53, v60, v61
	v_lshl_add_u64 v[54:55], v[68:69], 0, v[136:137]
	global_store_dwordx4 v[54:55], v[50:53], off sc1
	s_nop 0
	s_nop 0
	v_add_u32_e32 v51, 0x90, v138
	v_mad_i64_i32 v[52:53], s[26:27], v51, s75, v[142:143]
	s_waitcnt vmcnt(7)
; __device__ __forceinline__ float sigmoidf_(float x) { return __builtin_amdgcn_rcpf(1.f + __builtin_amdgcn_exp2f(-x * LOG2E)); }
; #define PG8_BAR __builtin_amdgcn_s_barrier()
; #define EPI_ROWS(...) _Pragma("unroll") for (int ai = 0; ai < 2; ++ai) _Pragma("unroll") for (int m = 0; m < 4; ++m) { const int row = row0 + ai * 128 + m * 16; __VA_ARGS__ __builtin_amdgcn_sched_barrier(0); }
; __device__ __forceinline__ u32x4 pack8(f32x4 a, f32x4 b) { u32x4 w; w.x = pk2(a[0], a[1]); w.y = pk2(a[2], a[3]); w.z = pk2(b[0], b[1]); w.w = pk2(b[2], b[3]); return w; }
; template <class Epi>
; __device__ __forceinline__ void gemm_phase(LAS unsigned char* lds, const Gemm g, const StaticOrder& S, const Epi& E) {
;     ...
;         if (!has_next) break;
; #pragma unroll
;         for (int a = 0; a < 2; ++a)
; #pragma unroll
;             for (int b = 0; b < 2; ++b)
; #pragma unroll
;                 for (int m = 0; m < 4; ++m)
; #pragma unroll
;                     for (int n = 0; n < 2; ++n) acc[a][b][m][n] = (f32x4){0.f, 0.f, 0.f, 0.f};
;         cur = nxt; cA = nA; cB = nB; ++ui;
;         if (wr == 1) PG8_BAR;
;     __device__ __forceinline__ void operator()(AccRef acc, const Unit& u, int wr, int wc, int fr, int fq) const {
;         const int row0 = u.pm * 256 + wr * 64 + fr, col0 = u.pn * 128 + wc * 32 + 8 * fq;
;         EPI_ROWS(
;             const float rs = __builtin_amdgcn_rsqf(ss[row] * (1.f / 1024.f) + EPS);
;             f32x4 o[2];
;             _Pragma("unroll") for (int n = 0; n < 2; ++n) _Pragma("unroll") for (int i = 0; i < 4; ++i) { const float gg = acc[ai][0][m][n][i] * rs, uu = acc[ai][1][m][n][i] * rs; o[n][i] = gg * sigmoidf_(gg) * uu; }
;             *(u32x4*)(H + (size_t)row * DFF + col0) = pack8(o[0], o[1]);
	v_fmamk_f32 v50, v189, 0x3a800000, v154
	v_rsq_f32_e32 v50, v50
	s_nop 0
	v_pk_mul_f32 v[46:47], v[46:47], v[50:51] op_sel_hi:[1,0]
	v_pk_mul_f32 v[48:49], v[48:49], v[50:51] op_sel_hi:[1,0]
	v_pk_mul_f32 v[42:43], v[42:43], v[50:51] op_sel_hi:[1,0]
	v_pk_mul_f32 v[44:45], v[44:45], v[50:51] op_sel_hi:[1,0]
	v_pk_mul_f32 v[38:39], v[38:39], v[50:51] op_sel_hi:[1,0]
	v_pk_mul_f32 v[40:41], v[40:41], v[50:51] op_sel_hi:[1,0]
	v_pk_mul_f32 v[34:35], v[34:35], v[50:51] op_sel_hi:[1,0]
	v_pk_mul_f32 v[36:37], v[36:37], v[50:51] op_sel_hi:[1,0]
	v_mul_f32_e32 v50, 0xbfb8aa3b, v46
	v_mul_f32_e32 v51, 0xbfb8aa3b, v47
	v_mul_f32_e32 v54, 0xbfb8aa3b, v48
	v_mul_f32_e32 v55, 0xbfb8aa3b, v49
	v_mul_f32_e32 v56, 0xbfb8aa3b, v42
	v_mul_f32_e32 v57, 0xbfb8aa3b, v43
	v_mul_f32_e32 v58, 0xbfb8aa3b, v44
	v_mul_f32_e32 v59, 0xbfb8aa3b, v45
	v_exp_f32_e32 v50, v50
	v_exp_f32_e32 v51, v51
	v_exp_f32_e32 v54, v54
	v_exp_f32_e32 v55, v55
	v_exp_f32_e32 v56, v56
	v_exp_f32_e32 v57, v57
	v_exp_f32_e32 v58, v58
	v_exp_f32_e32 v59, v59
	v_add_f32_e32 v50, 1.0, v50
	v_add_f32_e32 v51, 1.0, v51
	v_add_f32_e32 v54, 1.0, v54
	v_add_f32_e32 v55, 1.0, v55
	v_add_f32_e32 v56, 1.0, v56
	v_add_f32_e32 v57, 1.0, v57
	v_add_f32_e32 v58, 1.0, v58
	v_add_f32_e32 v59, 1.0, v59
	v_rcp_f32_e32 v50, v50
	v_rcp_f32_e32 v51, v51
	v_rcp_f32_e32 v54, v54
	v_rcp_f32_e32 v55, v55
	v_rcp_f32_e32 v56, v56
	v_rcp_f32_e32 v57, v57
	v_rcp_f32_e32 v58, v58
	v_rcp_f32_e32 v59, v59
	v_pk_mul_f32 v[46:47], v[46:47], v[50:51]
	v_pk_mul_f32 v[48:49], v[48:49], v[54:55]
	v_pk_mul_f32 v[42:43], v[42:43], v[56:57]
	v_pk_mul_f32 v[44:45], v[44:45], v[58:59]
	v_pk_mul_f32 v[38:39], v[38:39], v[46:47]
	v_pk_mul_f32 v[40:41], v[40:41], v[48:49]
	v_pk_mul_f32 v[42:43], v[34:35], v[42:43]
	v_pk_mul_f32 v[44:45], v[36:37], v[44:45]
	v_cvt_pk_bf16_f32 v34, v38, v39
	v_cvt_pk_bf16_f32 v35, v40, v41
	v_cvt_pk_bf16_f32 v36, v42, v43
	v_cvt_pk_bf16_f32 v37, v44, v45
	v_lshl_add_u64 v[38:39], v[52:53], 0, v[136:137]
	global_store_dwordx4 v[38:39], v[34:37], off sc1
	s_nop 0
	s_nop 0
	v_add_u32_e32 v35, 0xa0, v138
	v_mad_i64_i32 v[36:37], s[26:27], v35, s75, v[142:143]
	s_waitcnt vmcnt(7)
	v_fmamk_f32 v34, v190, 0x3a800000, v154
	v_rsq_f32_e32 v34, v34
	s_nop 0
	v_pk_mul_f32 v[30:31], v[30:31], v[34:35] op_sel_hi:[1,0]
	v_pk_mul_f32 v[32:33], v[32:33], v[34:35] op_sel_hi:[1,0]
	v_pk_mul_f32 v[26:27], v[26:27], v[34:35] op_sel_hi:[1,0]
	v_pk_mul_f32 v[28:29], v[28:29], v[34:35] op_sel_hi:[1,0]
	v_pk_mul_f32 v[22:23], v[22:23], v[34:35] op_sel_hi:[1,0]
	v_pk_mul_f32 v[24:25], v[24:25], v[34:35] op_sel_hi:[1,0]
	v_pk_mul_f32 v[18:19], v[18:19], v[34:35] op_sel_hi:[1,0]
	v_pk_mul_f32 v[20:21], v[20:21], v[34:35] op_sel_hi:[1,0]
	v_mul_f32_e32 v34, 0xbfb8aa3b, v30
	v_mul_f32_e32 v35, 0xbfb8aa3b, v31
	v_mul_f32_e32 v38, 0xbfb8aa3b, v32
	v_mul_f32_e32 v39, 0xbfb8aa3b, v33
	v_mul_f32_e32 v40, 0xbfb8aa3b, v26
	v_mul_f32_e32 v41, 0xbfb8aa3b, v27
	v_mul_f32_e32 v42, 0xbfb8aa3b, v28
	v_mul_f32_e32 v43, 0xbfb8aa3b, v29
	v_exp_f32_e32 v34, v34
	v_exp_f32_e32 v35, v35
	v_exp_f32_e32 v38, v38
	v_exp_f32_e32 v39, v39
	v_exp_f32_e32 v40, v40
	v_exp_f32_e32 v41, v41
	v_exp_f32_e32 v42, v42
	v_exp_f32_e32 v43, v43
	v_add_f32_e32 v34, 1.0, v34
	v_add_f32_e32 v35, 1.0, v35
	v_add_f32_e32 v38, 1.0, v38
	v_add_f32_e32 v39, 1.0, v39
	v_add_f32_e32 v40, 1.0, v40
	v_add_f32_e32 v41, 1.0, v41
	v_add_f32_e32 v42, 1.0, v42
	v_add_f32_e32 v43, 1.0, v43
	v_rcp_f32_e32 v34, v34
	v_rcp_f32_e32 v35, v35
	v_rcp_f32_e32 v38, v38
	v_rcp_f32_e32 v39, v39
	v_rcp_f32_e32 v40, v40
	v_rcp_f32_e32 v41, v41
	v_rcp_f32_e32 v42, v42
	v_rcp_f32_e32 v43, v43
	v_pk_mul_f32 v[30:31], v[30:31], v[34:35]
	v_pk_mul_f32 v[32:33], v[32:33], v[38:39]
	v_pk_mul_f32 v[26:27], v[26:27], v[40:41]
	v_pk_mul_f32 v[28:29], v[28:29], v[42:43]
	v_pk_mul_f32 v[22:23], v[22:23], v[30:31]
	v_pk_mul_f32 v[24:25], v[24:25], v[32:33]
	v_pk_mul_f32 v[26:27], v[18:19], v[26:27]
	v_pk_mul_f32 v[28:29], v[20:21], v[28:29]
	v_cvt_pk_bf16_f32 v18, v22, v23
	v_cvt_pk_bf16_f32 v19, v24, v25
	v_cvt_pk_bf16_f32 v20, v26, v27
	v_cvt_pk_bf16_f32 v21, v28, v29
	v_lshl_add_u64 v[22:23], v[36:37], 0, v[136:137]
	global_store_dwordx4 v[22:23], v[18:21], off sc1
	s_nop 0
	s_nop 0
	v_add_u32_e32 v19, 0xb0, v138
	v_mad_i64_i32 v[20:21], s[26:27], v19, s75, v[142:143]
	s_waitcnt vmcnt(7)
	v_fmamk_f32 v18, v191, 0x3a800000, v154
	v_rsq_f32_e32 v18, v18
	s_nop 0
	v_pk_mul_f32 v[14:15], v[14:15], v[18:19] op_sel_hi:[1,0]
	v_pk_mul_f32 v[16:17], v[16:17], v[18:19] op_sel_hi:[1,0]
	v_pk_mul_f32 v[10:11], v[10:11], v[18:19] op_sel_hi:[1,0]
	v_pk_mul_f32 v[12:13], v[12:13], v[18:19] op_sel_hi:[1,0]
	v_pk_mul_f32 v[6:7], v[6:7], v[18:19] op_sel_hi:[1,0]
	v_pk_mul_f32 v[8:9], v[8:9], v[18:19] op_sel_hi:[1,0]
	v_pk_mul_f32 v[2:3], v[2:3], v[18:19] op_sel_hi:[1,0]
	v_pk_mul_f32 v[4:5], v[4:5], v[18:19] op_sel_hi:[1,0]
	v_mul_f32_e32 v18, 0xbfb8aa3b, v14
	v_mul_f32_e32 v19, 0xbfb8aa3b, v15
	v_mul_f32_e32 v22, 0xbfb8aa3b, v16
	v_mul_f32_e32 v23, 0xbfb8aa3b, v17
	v_mul_f32_e32 v24, 0xbfb8aa3b, v10
	v_mul_f32_e32 v25, 0xbfb8aa3b, v11
	v_mul_f32_e32 v26, 0xbfb8aa3b, v12
	v_mul_f32_e32 v27, 0xbfb8aa3b, v13
	v_exp_f32_e32 v18, v18
	v_exp_f32_e32 v19, v19
	v_exp_f32_e32 v22, v22
	v_exp_f32_e32 v23, v23
	v_exp_f32_e32 v24, v24
	v_exp_f32_e32 v25, v25
	v_exp_f32_e32 v26, v26
	v_exp_f32_e32 v27, v27
	v_add_f32_e32 v18, 1.0, v18
	v_add_f32_e32 v19, 1.0, v19
	v_add_f32_e32 v22, 1.0, v22
	v_add_f32_e32 v23, 1.0, v23
	v_add_f32_e32 v24, 1.0, v24
	v_add_f32_e32 v25, 1.0, v25
	v_add_f32_e32 v26, 1.0, v26
	v_add_f32_e32 v27, 1.0, v27
	v_rcp_f32_e32 v18, v18
	v_rcp_f32_e32 v19, v19
	v_rcp_f32_e32 v22, v22
	v_rcp_f32_e32 v23, v23
	v_rcp_f32_e32 v24, v24
	v_rcp_f32_e32 v25, v25
	v_rcp_f32_e32 v26, v26
	v_rcp_f32_e32 v27, v27
	v_pk_mul_f32 v[14:15], v[14:15], v[18:19]
	v_pk_mul_f32 v[16:17], v[16:17], v[22:23]
	v_pk_mul_f32 v[10:11], v[10:11], v[24:25]
	v_pk_mul_f32 v[12:13], v[12:13], v[26:27]
	v_pk_mul_f32 v[6:7], v[6:7], v[14:15]
	v_pk_mul_f32 v[8:9], v[8:9], v[16:17]
	v_pk_mul_f32 v[10:11], v[2:3], v[10:11]
	v_pk_mul_f32 v[12:13], v[4:5], v[12:13]
	v_cvt_pk_bf16_f32 v2, v6, v7
	v_cvt_pk_bf16_f32 v3, v8, v9
	v_cvt_pk_bf16_f32 v4, v10, v11
	v_cvt_pk_bf16_f32 v5, v12, v13
	v_lshl_add_u64 v[6:7], v[20:21], 0, v[136:137]
	global_store_dwordx4 v[6:7], v[2:5], off sc1
	s_andn2_b64 vcc, exec, s[0:1]
	s_mov_b64 s[0:1], -1
	v_readlane_b32 s86, v255, 31
	v_readlane_b32 s87, v255, 32
	s_cbranch_vccnz .LBB0_196
	s_andn2_b64 vcc, exec, s[4:5]
	s_cbranch_vccnz .LBB0_195
	s_barrier
	s_branch .LBB0_195

; __device__ __forceinline__ float sigmoidf_(float x) { return __builtin_amdgcn_rcpf(1.f + __builtin_amdgcn_exp2f(-x * LOG2E)); }
; #define EPI_ROWS(...) _Pragma("unroll") for (int ai = 0; ai < 2; ++ai) _Pragma("unroll") for (int m = 0; m < 4; ++m) { const int row = row0 + ai * 128 + m * 16; __VA_ARGS__ __builtin_amdgcn_sched_barrier(0); }
; __device__ __forceinline__ u32x4 pack8(f32x4 a, f32x4 b) { u32x4 w; w.x = pk2(a[0], a[1]); w.y = pk2(a[2], a[3]); w.z = pk2(b[0], b[1]); w.w = pk2(b[2], b[3]); return w; }
;     __device__ __forceinline__ void operator()(AccRef acc, const Unit& u, int wr, int wc, int fr, int fq) const {
;         const int row0 = u.pm * 256 + wr * 64 + fr, col0 = u.pn * 128 + wc * 32 + 8 * fq;
;         EPI_ROWS(
;             const float rs = __builtin_amdgcn_rsqf(ss[row] * (1.f / 1024.f) + EPS);
;             f32x4 o[2];
;             _Pragma("unroll") for (int n = 0; n < 2; ++n) _Pragma("unroll") for (int i = 0; i < 4; ++i) { const float gg = acc[ai][0][m][n][i] * rs, uu = acc[ai][1][m][n][i] * rs; o[n][i] = gg * sigmoidf_(gg) * uu; }
;             *(u32x4*)(H + (size_t)row * DFF + col0) = pack8(o[0], o[1]);
;         )
;     }
.LBB0_1519:
	v_lshl_add_u32 v136, s38, 8, v147
	v_ashrrev_i32_e32 v137, 31, v136
	v_lshl_add_u64 v[138:139], v[136:137], 2, s[12:13]
	global_load_dword v184, v[138:139], off
	global_load_dword v185, v[138:139], off offset:64
	global_load_dword v186, v[138:139], off offset:128
	global_load_dword v187, v[138:139], off offset:192
	global_load_dword v188, v[138:139], off offset:512
	global_load_dword v189, v[138:139], off offset:576
	global_load_dword v190, v[138:139], off offset:640
	global_load_dword v191, v[138:139], off offset:704
	v_lshl_or_b32 v134, s60, 7, v148
	v_mov_b64_e32 v[142:143], s[24:25]
	v_ashrrev_i32_e32 v135, 31, v134
	v_mad_i64_i32 v[158:159], s[16:17], v136, s59, v[142:143]
	v_lshlrev_b64 v[134:135], 1, v[134:135]
	s_waitcnt vmcnt(7)
	v_fmamk_f32 v137, v184, 0x3a800000, v154
	v_rsq_f32_e32 v156, v137
	s_nop 0
	v_pk_mul_f32 v[126:127], v[126:127], v[156:157] op_sel_hi:[1,0]
	v_pk_mul_f32 v[128:129], v[128:129], v[156:157] op_sel_hi:[1,0]
	v_pk_mul_f32 v[122:123], v[122:123], v[156:157] op_sel_hi:[1,0]
	v_pk_mul_f32 v[124:125], v[124:125], v[156:157] op_sel_hi:[1,0]
	v_pk_mul_f32 v[118:119], v[118:119], v[156:157] op_sel_hi:[1,0]
	v_pk_mul_f32 v[120:121], v[120:121], v[156:157] op_sel_hi:[1,0]
	v_pk_mul_f32 v[114:115], v[114:115], v[156:157] op_sel_hi:[1,0]
	v_pk_mul_f32 v[116:117], v[116:117], v[156:157] op_sel_hi:[1,0]
	v_mul_f32_e32 v137, 0xbfb8aa3b, v126
	v_mul_f32_e32 v155, 0xbfb8aa3b, v127
	v_mul_f32_e32 v156, 0xbfb8aa3b, v128
	v_mul_f32_e32 v157, 0xbfb8aa3b, v129
	v_mul_f32_e32 v160, 0xbfb8aa3b, v122
	v_mul_f32_e32 v161, 0xbfb8aa3b, v123
	v_mul_f32_e32 v162, 0xbfb8aa3b, v124
	v_mul_f32_e32 v163, 0xbfb8aa3b, v125
	v_exp_f32_e32 v137, v137
	v_exp_f32_e32 v155, v155
	v_exp_f32_e32 v156, v156
	v_exp_f32_e32 v157, v157
	v_exp_f32_e32 v160, v160
	v_exp_f32_e32 v161, v161
	v_exp_f32_e32 v162, v162
	v_exp_f32_e32 v163, v163
	v_add_f32_e32 v137, 1.0, v137
	v_add_f32_e32 v155, 1.0, v155
	v_add_f32_e32 v164, 1.0, v156
	v_add_f32_e32 v165, 1.0, v157
	v_add_f32_e32 v166, 1.0, v160
	v_add_f32_e32 v167, 1.0, v161
	v_add_f32_e32 v168, 1.0, v162
	v_add_f32_e32 v169, 1.0, v163
	v_rcp_f32_e32 v156, v137
	v_rcp_f32_e32 v157, v155
	v_rcp_f32_e32 v160, v164
	v_rcp_f32_e32 v161, v165
	v_rcp_f32_e32 v162, v166
	v_rcp_f32_e32 v163, v167
	v_rcp_f32_e32 v164, v168
	v_rcp_f32_e32 v165, v169
	v_pk_mul_f32 v[126:127], v[126:127], v[156:157]
	v_pk_mul_f32 v[128:129], v[128:129], v[160:161]
	v_pk_mul_f32 v[122:123], v[122:123], v[162:163]
	v_pk_mul_f32 v[124:125], v[124:125], v[164:165]
	v_pk_mul_f32 v[118:119], v[118:119], v[126:127]
	v_pk_mul_f32 v[120:121], v[120:121], v[128:129]
	v_pk_mul_f32 v[122:123], v[114:115], v[122:123]
	v_pk_mul_f32 v[124:125], v[116:117], v[124:125]
	v_cvt_pk_bf16_f32 v114, v118, v119
	v_cvt_pk_bf16_f32 v115, v120, v121
	v_cvt_pk_bf16_f32 v116, v122, v123
	v_cvt_pk_bf16_f32 v117, v124, v125
	v_lshl_add_u64 v[118:119], v[158:159], 0, v[134:135]
	global_store_dwordx4 v[118:119], v[114:117], off sc1
	s_nop 1
	v_or_b32_e32 v114, 16, v136
	v_ashrrev_i32_e32 v115, 31, v114
	v_lshl_add_u64 v[116:117], v[114:115], 2, s[12:13]
	s_nop 0
	s_waitcnt vmcnt(7)
	v_fmamk_f32 v115, v185, 0x3a800000, v154
	v_rsq_f32_e32 v116, v115
	v_mad_i64_i32 v[114:115], s[16:17], v114, s59, v[142:143]
	v_pk_mul_f32 v[110:111], v[110:111], v[116:117] op_sel_hi:[1,0]
	v_pk_mul_f32 v[112:113], v[112:113], v[116:117] op_sel_hi:[1,0]
	v_pk_mul_f32 v[106:107], v[106:107], v[116:117] op_sel_hi:[1,0]
	v_pk_mul_f32 v[108:109], v[108:109], v[116:117] op_sel_hi:[1,0]
	v_pk_mul_f32 v[102:103], v[102:103], v[116:117] op_sel_hi:[1,0]
	v_pk_mul_f32 v[104:105], v[104:105], v[116:117] op_sel_hi:[1,0]
	v_pk_mul_f32 v[98:99], v[98:99], v[116:117] op_sel_hi:[1,0]
	v_pk_mul_f32 v[100:101], v[100:101], v[116:117] op_sel_hi:[1,0]
	v_mul_f32_e32 v116, 0xbfb8aa3b, v110
	v_mul_f32_e32 v117, 0xbfb8aa3b, v111
	v_mul_f32_e32 v118, 0xbfb8aa3b, v112
	v_mul_f32_e32 v119, 0xbfb8aa3b, v113
	v_mul_f32_e32 v120, 0xbfb8aa3b, v106
	v_mul_f32_e32 v121, 0xbfb8aa3b, v107
	v_mul_f32_e32 v122, 0xbfb8aa3b, v108
	v_mul_f32_e32 v123, 0xbfb8aa3b, v109
	v_exp_f32_e32 v116, v116
	v_exp_f32_e32 v117, v117
	v_exp_f32_e32 v118, v118
	v_exp_f32_e32 v119, v119
	v_exp_f32_e32 v120, v120
	v_exp_f32_e32 v121, v121
	v_exp_f32_e32 v122, v122
	v_exp_f32_e32 v123, v123
	v_add_f32_e32 v116, 1.0, v116
	v_add_f32_e32 v117, 1.0, v117
	v_add_f32_e32 v118, 1.0, v118
	v_add_f32_e32 v119, 1.0, v119
	v_add_f32_e32 v120, 1.0, v120
	v_add_f32_e32 v121, 1.0, v121
	v_add_f32_e32 v122, 1.0, v122
	v_add_f32_e32 v123, 1.0, v123
	v_rcp_f32_e32 v116, v116
	v_rcp_f32_e32 v117, v117
	v_rcp_f32_e32 v118, v118
	v_rcp_f32_e32 v119, v119
	v_rcp_f32_e32 v120, v120
	v_rcp_f32_e32 v121, v121
	v_rcp_f32_e32 v122, v122
	v_rcp_f32_e32 v123, v123
	v_pk_mul_f32 v[110:111], v[110:111], v[116:117]
	v_pk_mul_f32 v[112:113], v[112:113], v[118:119]
	v_pk_mul_f32 v[106:107], v[106:107], v[120:121]
	v_pk_mul_f32 v[108:109], v[108:109], v[122:123]
	v_pk_mul_f32 v[102:103], v[102:103], v[110:111]
	v_pk_mul_f32 v[104:105], v[104:105], v[112:113]
	v_pk_mul_f32 v[106:107], v[98:99], v[106:107]
	v_pk_mul_f32 v[108:109], v[100:101], v[108:109]
	v_cvt_pk_bf16_f32 v98, v102, v103
	v_cvt_pk_bf16_f32 v99, v104, v105
	v_cvt_pk_bf16_f32 v100, v106, v107
	v_cvt_pk_bf16_f32 v101, v108, v109
	v_lshl_add_u64 v[102:103], v[114:115], 0, v[134:135]
	global_store_dwordx4 v[102:103], v[98:101], off sc1
	s_nop 1
	v_or_b32_e32 v98, 32, v136
	v_ashrrev_i32_e32 v99, 31, v98
	v_lshl_add_u64 v[100:101], v[98:99], 2, s[12:13]
	s_nop 0
	s_waitcnt vmcnt(7)
; __device__ __forceinline__ float sigmoidf_(float x) { return __builtin_amdgcn_rcpf(1.f + __builtin_amdgcn_exp2f(-x * LOG2E)); }
; #define EPI_ROWS(...) _Pragma("unroll") for (int ai = 0; ai < 2; ++ai) _Pragma("unroll") for (int m = 0; m < 4; ++m) { const int row = row0 + ai * 128 + m * 16; __VA_ARGS__ __builtin_amdgcn_sched_barrier(0); }
; __device__ __forceinline__ u32x4 pack8(f32x4 a, f32x4 b) { u32x4 w; w.x = pk2(a[0], a[1]); w.y = pk2(a[2], a[3]); w.z = pk2(b[0], b[1]); w.w = pk2(b[2], b[3]); return w; }
;     __device__ __forceinline__ void operator()(AccRef acc, const Unit& u, int wr, int wc, int fr, int fq) const {
;         const int row0 = u.pm * 256 + wr * 64 + fr, col0 = u.pn * 128 + wc * 32 + 8 * fq;
;         EPI_ROWS(
;             const float rs = __builtin_amdgcn_rsqf(ss[row] * (1.f / 1024.f) + EPS);
;             f32x4 o[2];
;             _Pragma("unroll") for (int n = 0; n < 2; ++n) _Pragma("unroll") for (int i = 0; i < 4; ++i) { const float gg = acc[ai][0][m][n][i] * rs, uu = acc[ai][1][m][n][i] * rs; o[n][i] = gg * sigmoidf_(gg) * uu; }
;             *(u32x4*)(H + (size_t)row * DFF + col0) = pack8(o[0], o[1]);
;         )
;     }
	v_fmamk_f32 v99, v186, 0x3a800000, v154
	v_rsq_f32_e32 v100, v99
	v_mad_i64_i32 v[98:99], s[16:17], v98, s59, v[142:143]
	v_pk_mul_f32 v[94:95], v[94:95], v[100:101] op_sel_hi:[1,0]
	v_pk_mul_f32 v[96:97], v[96:97], v[100:101] op_sel_hi:[1,0]
	v_pk_mul_f32 v[90:91], v[90:91], v[100:101] op_sel_hi:[1,0]
	v_pk_mul_f32 v[92:93], v[92:93], v[100:101] op_sel_hi:[1,0]
	v_pk_mul_f32 v[86:87], v[86:87], v[100:101] op_sel_hi:[1,0]
	v_pk_mul_f32 v[88:89], v[88:89], v[100:101] op_sel_hi:[1,0]
	v_pk_mul_f32 v[82:83], v[82:83], v[100:101] op_sel_hi:[1,0]
	v_pk_mul_f32 v[84:85], v[84:85], v[100:101] op_sel_hi:[1,0]
	v_mul_f32_e32 v100, 0xbfb8aa3b, v94
	v_mul_f32_e32 v101, 0xbfb8aa3b, v95
	v_mul_f32_e32 v102, 0xbfb8aa3b, v96
	v_mul_f32_e32 v103, 0xbfb8aa3b, v97
	v_mul_f32_e32 v104, 0xbfb8aa3b, v90
	v_mul_f32_e32 v105, 0xbfb8aa3b, v91
	v_mul_f32_e32 v106, 0xbfb8aa3b, v92
	v_mul_f32_e32 v107, 0xbfb8aa3b, v93
	v_exp_f32_e32 v100, v100
	v_exp_f32_e32 v101, v101
	v_exp_f32_e32 v102, v102
	v_exp_f32_e32 v103, v103
	v_exp_f32_e32 v104, v104
	v_exp_f32_e32 v105, v105
	v_exp_f32_e32 v106, v106
	v_exp_f32_e32 v107, v107
	v_add_f32_e32 v100, 1.0, v100
	v_add_f32_e32 v101, 1.0, v101
	v_add_f32_e32 v102, 1.0, v102
	v_add_f32_e32 v103, 1.0, v103
	v_add_f32_e32 v104, 1.0, v104
	v_add_f32_e32 v105, 1.0, v105
	v_add_f32_e32 v106, 1.0, v106
	v_add_f32_e32 v107, 1.0, v107
	v_rcp_f32_e32 v100, v100
	v_rcp_f32_e32 v101, v101
	v_rcp_f32_e32 v102, v102
	v_rcp_f32_e32 v103, v103
	v_rcp_f32_e32 v104, v104
	v_rcp_f32_e32 v105, v105
	v_rcp_f32_e32 v106, v106
	v_rcp_f32_e32 v107, v107
	v_pk_mul_f32 v[94:95], v[94:95], v[100:101]
	v_pk_mul_f32 v[96:97], v[96:97], v[102:103]
	v_pk_mul_f32 v[90:91], v[90:91], v[104:105]
	v_pk_mul_f32 v[92:93], v[92:93], v[106:107]
	v_pk_mul_f32 v[86:87], v[86:87], v[94:95]
	v_pk_mul_f32 v[88:89], v[88:89], v[96:97]
	v_pk_mul_f32 v[90:91], v[82:83], v[90:91]
	v_pk_mul_f32 v[92:93], v[84:85], v[92:93]
	v_cvt_pk_bf16_f32 v82, v86, v87
	v_cvt_pk_bf16_f32 v83, v88, v89
	v_cvt_pk_bf16_f32 v84, v90, v91
	v_cvt_pk_bf16_f32 v85, v92, v93
	v_lshl_add_u64 v[86:87], v[98:99], 0, v[134:135]
	global_store_dwordx4 v[86:87], v[82:85], off sc1
	s_nop 1
	v_or_b32_e32 v82, 48, v136
	v_ashrrev_i32_e32 v83, 31, v82
	v_lshl_add_u64 v[84:85], v[82:83], 2, s[12:13]
	s_nop 0
	s_waitcnt vmcnt(7)
	v_fmamk_f32 v83, v187, 0x3a800000, v154
	v_rsq_f32_e32 v84, v83
	v_mad_i64_i32 v[82:83], s[16:17], v82, s59, v[142:143]
	v_pk_mul_f32 v[78:79], v[78:79], v[84:85] op_sel_hi:[1,0]
	v_pk_mul_f32 v[80:81], v[80:81], v[84:85] op_sel_hi:[1,0]
	v_pk_mul_f32 v[74:75], v[74:75], v[84:85] op_sel_hi:[1,0]
	v_pk_mul_f32 v[76:77], v[76:77], v[84:85] op_sel_hi:[1,0]
	v_pk_mul_f32 v[70:71], v[70:71], v[84:85] op_sel_hi:[1,0]
	v_pk_mul_f32 v[72:73], v[72:73], v[84:85] op_sel_hi:[1,0]
	v_pk_mul_f32 v[66:67], v[66:67], v[84:85] op_sel_hi:[1,0]
	v_pk_mul_f32 v[68:69], v[68:69], v[84:85] op_sel_hi:[1,0]
	v_mul_f32_e32 v84, 0xbfb8aa3b, v78
	v_mul_f32_e32 v85, 0xbfb8aa3b, v79
	v_mul_f32_e32 v86, 0xbfb8aa3b, v80
	v_mul_f32_e32 v87, 0xbfb8aa3b, v81
	v_mul_f32_e32 v88, 0xbfb8aa3b, v74
	v_mul_f32_e32 v89, 0xbfb8aa3b, v75
	v_mul_f32_e32 v90, 0xbfb8aa3b, v76
	v_mul_f32_e32 v91, 0xbfb8aa3b, v77
	v_exp_f32_e32 v84, v84
	v_exp_f32_e32 v85, v85
	v_exp_f32_e32 v86, v86
	v_exp_f32_e32 v87, v87
	v_exp_f32_e32 v88, v88
	v_exp_f32_e32 v89, v89
	v_exp_f32_e32 v90, v90
	v_exp_f32_e32 v91, v91
	v_add_f32_e32 v84, 1.0, v84
	v_add_f32_e32 v85, 1.0, v85
	v_add_f32_e32 v86, 1.0, v86
	v_add_f32_e32 v87, 1.0, v87
	v_add_f32_e32 v88, 1.0, v88
	v_add_f32_e32 v89, 1.0, v89
	v_add_f32_e32 v90, 1.0, v90
	v_add_f32_e32 v91, 1.0, v91
	v_rcp_f32_e32 v84, v84
	v_rcp_f32_e32 v85, v85
	v_rcp_f32_e32 v86, v86
	v_rcp_f32_e32 v87, v87
	v_rcp_f32_e32 v88, v88
	v_rcp_f32_e32 v89, v89
	v_rcp_f32_e32 v90, v90
	v_rcp_f32_e32 v91, v91
	v_pk_mul_f32 v[78:79], v[78:79], v[84:85]
	v_pk_mul_f32 v[80:81], v[80:81], v[86:87]
	v_pk_mul_f32 v[74:75], v[74:75], v[88:89]
	v_pk_mul_f32 v[76:77], v[76:77], v[90:91]
	v_pk_mul_f32 v[70:71], v[70:71], v[78:79]
	v_pk_mul_f32 v[72:73], v[72:73], v[80:81]
	v_pk_mul_f32 v[74:75], v[66:67], v[74:75]
	v_pk_mul_f32 v[76:77], v[68:69], v[76:77]
	v_cvt_pk_bf16_f32 v66, v70, v71
	v_cvt_pk_bf16_f32 v67, v72, v73
	v_cvt_pk_bf16_f32 v68, v74, v75
	v_cvt_pk_bf16_f32 v69, v76, v77
	v_lshl_add_u64 v[70:71], v[82:83], 0, v[134:135]
	global_store_dwordx4 v[70:71], v[66:69], off sc1
	s_nop 0
	s_nop 0
	v_add_u32_e32 v67, 0x80, v136
	v_mad_i64_i32 v[68:69], s[16:17], v67, s59, v[142:143]
	s_waitcnt vmcnt(7)
	v_fmamk_f32 v66, v188, 0x3a800000, v154
	v_rsq_f32_e32 v66, v66
	s_nop 0
	v_pk_mul_f32 v[62:63], v[62:63], v[66:67] op_sel_hi:[1,0]
	v_pk_mul_f32 v[64:65], v[64:65], v[66:67] op_sel_hi:[1,0]
	v_pk_mul_f32 v[58:59], v[58:59], v[66:67] op_sel_hi:[1,0]
	v_pk_mul_f32 v[60:61], v[60:61], v[66:67] op_sel_hi:[1,0]
	v_pk_mul_f32 v[54:55], v[54:55], v[66:67] op_sel_hi:[1,0]
	v_pk_mul_f32 v[56:57], v[56:57], v[66:67] op_sel_hi:[1,0]
	v_pk_mul_f32 v[50:51], v[50:51], v[66:67] op_sel_hi:[1,0]
	v_pk_mul_f32 v[52:53], v[52:53], v[66:67] op_sel_hi:[1,0]
	v_mul_f32_e32 v66, 0xbfb8aa3b, v62
	v_mul_f32_e32 v67, 0xbfb8aa3b, v63
	v_mul_f32_e32 v70, 0xbfb8aa3b, v64
	v_mul_f32_e32 v71, 0xbfb8aa3b, v65
	v_mul_f32_e32 v72, 0xbfb8aa3b, v58
	v_mul_f32_e32 v73, 0xbfb8aa3b, v59
	v_mul_f32_e32 v74, 0xbfb8aa3b, v60
	v_mul_f32_e32 v75, 0xbfb8aa3b, v61
	v_exp_f32_e32 v66, v66
	v_exp_f32_e32 v67, v67
	v_exp_f32_e32 v70, v70
	v_exp_f32_e32 v71, v71
	v_exp_f32_e32 v72, v72
	v_exp_f32_e32 v73, v73
	v_exp_f32_e32 v74, v74
	v_exp_f32_e32 v75, v75
	v_add_f32_e32 v66, 1.0, v66
	v_add_f32_e32 v67, 1.0, v67
	v_add_f32_e32 v70, 1.0, v70
	v_add_f32_e32 v71, 1.0, v71
	v_add_f32_e32 v72, 1.0, v72
	v_add_f32_e32 v73, 1.0, v73
	v_add_f32_e32 v74, 1.0, v74
	v_add_f32_e32 v75, 1.0, v75
	v_rcp_f32_e32 v66, v66
	v_rcp_f32_e32 v67, v67
	v_rcp_f32_e32 v70, v70
	v_rcp_f32_e32 v71, v71
	v_rcp_f32_e32 v72, v72
	v_rcp_f32_e32 v73, v73
	v_rcp_f32_e32 v74, v74
	v_rcp_f32_e32 v75, v75
	v_pk_mul_f32 v[62:63], v[62:63], v[66:67]
	v_pk_mul_f32 v[64:65], v[64:65], v[70:71]
	v_pk_mul_f32 v[58:59], v[58:59], v[72:73]
	v_pk_mul_f32 v[60:61], v[60:61], v[74:75]
	v_pk_mul_f32 v[54:55], v[54:55], v[62:63]
	v_pk_mul_f32 v[56:57], v[56:57], v[64:65]
	v_pk_mul_f32 v[58:59], v[50:51], v[58:59]
	v_pk_mul_f32 v[60:61], v[52:53], v[60:61]
	v_cvt_pk_bf16_f32 v50, v54, v55
	v_cvt_pk_bf16_f32 v51, v56, v57
	v_cvt_pk_bf16_f32 v52, v58, v59
	v_cvt_pk_bf16_f32 v53, v60, v61
	v_lshl_add_u64 v[54:55], v[68:69], 0, v[134:135]
	global_store_dwordx4 v[54:55], v[50:53], off sc1
	s_nop 0
	s_nop 0
	v_add_u32_e32 v51, 0x90, v136
	v_mad_i64_i32 v[52:53], s[16:17], v51, s59, v[142:143]
	s_waitcnt vmcnt(7)
; __device__ __forceinline__ float sigmoidf_(float x) { return __builtin_amdgcn_rcpf(1.f + __builtin_amdgcn_exp2f(-x * LOG2E)); }
; #define PG8_BAR __builtin_amdgcn_s_barrier()
; #define EPI_ROWS(...) _Pragma("unroll") for (int ai = 0; ai < 2; ++ai) _Pragma("unroll") for (int m = 0; m < 4; ++m) { const int row = row0 + ai * 128 + m * 16; __VA_ARGS__ __builtin_amdgcn_sched_barrier(0); }
; __device__ __forceinline__ u32x4 pack8(f32x4 a, f32x4 b) { u32x4 w; w.x = pk2(a[0], a[1]); w.y = pk2(a[2], a[3]); w.z = pk2(b[0], b[1]); w.w = pk2(b[2], b[3]); return w; }
; template <class Epi>
; __device__ __forceinline__ void gemm_phase(LAS unsigned char* lds, const Gemm g, const StaticOrder& S, const Epi& E) {
;     ...
;         if (!has_next) break;
; #pragma unroll
;         for (int a = 0; a < 2; ++a)
; #pragma unroll
;             for (int b = 0; b < 2; ++b)
; #pragma unroll
;                 for (int m = 0; m < 4; ++m)
; #pragma unroll
;                     for (int n = 0; n < 2; ++n) acc[a][b][m][n] = (f32x4){0.f, 0.f, 0.f, 0.f};
;         cur = nxt; cA = nA; cB = nB; ++ui;
;         if (wr == 1) PG8_BAR;
;     __device__ __forceinline__ void operator()(AccRef acc, const Unit& u, int wr, int wc, int fr, int fq) const {
;         const int row0 = u.pm * 256 + wr * 64 + fr, col0 = u.pn * 128 + wc * 32 + 8 * fq;
;         EPI_ROWS(
;             const float rs = __builtin_amdgcn_rsqf(ss[row] * (1.f / 1024.f) + EPS);
;             f32x4 o[2];
;             _Pragma("unroll") for (int n = 0; n < 2; ++n) _Pragma("unroll") for (int i = 0; i < 4; ++i) { const float gg = acc[ai][0][m][n][i] * rs, uu = acc[ai][1][m][n][i] * rs; o[n][i] = gg * sigmoidf_(gg) * uu; }
;             *(u32x4*)(H + (size_t)row * DFF + col0) = pack8(o[0], o[1]);
	v_fmamk_f32 v50, v189, 0x3a800000, v154
	v_rsq_f32_e32 v50, v50
	s_nop 0
	v_pk_mul_f32 v[46:47], v[46:47], v[50:51] op_sel_hi:[1,0]
	v_pk_mul_f32 v[48:49], v[48:49], v[50:51] op_sel_hi:[1,0]
	v_pk_mul_f32 v[42:43], v[42:43], v[50:51] op_sel_hi:[1,0]
	v_pk_mul_f32 v[44:45], v[44:45], v[50:51] op_sel_hi:[1,0]
	v_pk_mul_f32 v[38:39], v[38:39], v[50:51] op_sel_hi:[1,0]
	v_pk_mul_f32 v[40:41], v[40:41], v[50:51] op_sel_hi:[1,0]
	v_pk_mul_f32 v[34:35], v[34:35], v[50:51] op_sel_hi:[1,0]
	v_pk_mul_f32 v[36:37], v[36:37], v[50:51] op_sel_hi:[1,0]
	v_mul_f32_e32 v50, 0xbfb8aa3b, v46
	v_mul_f32_e32 v51, 0xbfb8aa3b, v47
	v_mul_f32_e32 v54, 0xbfb8aa3b, v48
	v_mul_f32_e32 v55, 0xbfb8aa3b, v49
	v_mul_f32_e32 v56, 0xbfb8aa3b, v42
	v_mul_f32_e32 v57, 0xbfb8aa3b, v43
	v_mul_f32_e32 v58, 0xbfb8aa3b, v44
	v_mul_f32_e32 v59, 0xbfb8aa3b, v45
	v_exp_f32_e32 v50, v50
	v_exp_f32_e32 v51, v51
	v_exp_f32_e32 v54, v54
	v_exp_f32_e32 v55, v55
	v_exp_f32_e32 v56, v56
	v_exp_f32_e32 v57, v57
	v_exp_f32_e32 v58, v58
	v_exp_f32_e32 v59, v59
	v_add_f32_e32 v50, 1.0, v50
	v_add_f32_e32 v51, 1.0, v51
	v_add_f32_e32 v54, 1.0, v54
	v_add_f32_e32 v55, 1.0, v55
	v_add_f32_e32 v56, 1.0, v56
	v_add_f32_e32 v57, 1.0, v57
	v_add_f32_e32 v58, 1.0, v58
	v_add_f32_e32 v59, 1.0, v59
	v_rcp_f32_e32 v50, v50
	v_rcp_f32_e32 v51, v51
	v_rcp_f32_e32 v54, v54
	v_rcp_f32_e32 v55, v55
	v_rcp_f32_e32 v56, v56
	v_rcp_f32_e32 v57, v57
	v_rcp_f32_e32 v58, v58
	v_rcp_f32_e32 v59, v59
	v_pk_mul_f32 v[46:47], v[46:47], v[50:51]
	v_pk_mul_f32 v[48:49], v[48:49], v[54:55]
	v_pk_mul_f32 v[42:43], v[42:43], v[56:57]
	v_pk_mul_f32 v[44:45], v[44:45], v[58:59]
	v_pk_mul_f32 v[38:39], v[38:39], v[46:47]
	v_pk_mul_f32 v[40:41], v[40:41], v[48:49]
	v_pk_mul_f32 v[42:43], v[34:35], v[42:43]
	v_pk_mul_f32 v[44:45], v[36:37], v[44:45]
	v_cvt_pk_bf16_f32 v34, v38, v39
	v_cvt_pk_bf16_f32 v35, v40, v41
	v_cvt_pk_bf16_f32 v36, v42, v43
	v_cvt_pk_bf16_f32 v37, v44, v45
	v_lshl_add_u64 v[38:39], v[52:53], 0, v[134:135]
	global_store_dwordx4 v[38:39], v[34:37], off sc1
	s_nop 0
	s_nop 0
	v_add_u32_e32 v35, 0xa0, v136
	v_mad_i64_i32 v[36:37], s[16:17], v35, s59, v[142:143]
	s_waitcnt vmcnt(7)
	v_fmamk_f32 v34, v190, 0x3a800000, v154
	v_rsq_f32_e32 v34, v34
	s_nop 0
	v_pk_mul_f32 v[30:31], v[30:31], v[34:35] op_sel_hi:[1,0]
	v_pk_mul_f32 v[32:33], v[32:33], v[34:35] op_sel_hi:[1,0]
	v_pk_mul_f32 v[26:27], v[26:27], v[34:35] op_sel_hi:[1,0]
	v_pk_mul_f32 v[28:29], v[28:29], v[34:35] op_sel_hi:[1,0]
	v_pk_mul_f32 v[22:23], v[22:23], v[34:35] op_sel_hi:[1,0]
	v_pk_mul_f32 v[24:25], v[24:25], v[34:35] op_sel_hi:[1,0]
	v_pk_mul_f32 v[18:19], v[18:19], v[34:35] op_sel_hi:[1,0]
	v_pk_mul_f32 v[20:21], v[20:21], v[34:35] op_sel_hi:[1,0]
	v_mul_f32_e32 v34, 0xbfb8aa3b, v30
	v_mul_f32_e32 v35, 0xbfb8aa3b, v31
	v_mul_f32_e32 v38, 0xbfb8aa3b, v32
	v_mul_f32_e32 v39, 0xbfb8aa3b, v33
	v_mul_f32_e32 v40, 0xbfb8aa3b, v26
	v_mul_f32_e32 v41, 0xbfb8aa3b, v27
	v_mul_f32_e32 v42, 0xbfb8aa3b, v28
	v_mul_f32_e32 v43, 0xbfb8aa3b, v29
	v_exp_f32_e32 v34, v34
	v_exp_f32_e32 v35, v35
	v_exp_f32_e32 v38, v38
	v_exp_f32_e32 v39, v39
	v_exp_f32_e32 v40, v40
	v_exp_f32_e32 v41, v41
	v_exp_f32_e32 v42, v42
	v_exp_f32_e32 v43, v43
	v_add_f32_e32 v34, 1.0, v34
	v_add_f32_e32 v35, 1.0, v35
	v_add_f32_e32 v38, 1.0, v38
	v_add_f32_e32 v39, 1.0, v39
	v_add_f32_e32 v40, 1.0, v40
	v_add_f32_e32 v41, 1.0, v41
	v_add_f32_e32 v42, 1.0, v42
	v_add_f32_e32 v43, 1.0, v43
	v_rcp_f32_e32 v34, v34
	v_rcp_f32_e32 v35, v35
	v_rcp_f32_e32 v38, v38
	v_rcp_f32_e32 v39, v39
	v_rcp_f32_e32 v40, v40
	v_rcp_f32_e32 v41, v41
	v_rcp_f32_e32 v42, v42
	v_rcp_f32_e32 v43, v43
	v_pk_mul_f32 v[30:31], v[30:31], v[34:35]
	v_pk_mul_f32 v[32:33], v[32:33], v[38:39]
	v_pk_mul_f32 v[26:27], v[26:27], v[40:41]
	v_pk_mul_f32 v[28:29], v[28:29], v[42:43]
	v_pk_mul_f32 v[22:23], v[22:23], v[30:31]
	v_pk_mul_f32 v[24:25], v[24:25], v[32:33]
	v_pk_mul_f32 v[26:27], v[18:19], v[26:27]
	v_pk_mul_f32 v[28:29], v[20:21], v[28:29]
	v_cvt_pk_bf16_f32 v18, v22, v23
	v_cvt_pk_bf16_f32 v19, v24, v25
	v_cvt_pk_bf16_f32 v20, v26, v27
	v_cvt_pk_bf16_f32 v21, v28, v29
	v_lshl_add_u64 v[22:23], v[36:37], 0, v[134:135]
	global_store_dwordx4 v[22:23], v[18:21], off sc1
	s_nop 0
	s_nop 0
	v_add_u32_e32 v19, 0xb0, v136
	v_mad_i64_i32 v[20:21], s[16:17], v19, s59, v[142:143]
	s_waitcnt vmcnt(7)
	v_fmamk_f32 v18, v191, 0x3a800000, v154
	v_rsq_f32_e32 v18, v18
	s_nop 0
	v_pk_mul_f32 v[14:15], v[14:15], v[18:19] op_sel_hi:[1,0]
	v_pk_mul_f32 v[16:17], v[16:17], v[18:19] op_sel_hi:[1,0]
	v_pk_mul_f32 v[10:11], v[10:11], v[18:19] op_sel_hi:[1,0]
	v_pk_mul_f32 v[12:13], v[12:13], v[18:19] op_sel_hi:[1,0]
	v_pk_mul_f32 v[6:7], v[6:7], v[18:19] op_sel_hi:[1,0]
	v_pk_mul_f32 v[8:9], v[8:9], v[18:19] op_sel_hi:[1,0]
	v_pk_mul_f32 v[2:3], v[2:3], v[18:19] op_sel_hi:[1,0]
	v_pk_mul_f32 v[4:5], v[4:5], v[18:19] op_sel_hi:[1,0]
	v_mul_f32_e32 v18, 0xbfb8aa3b, v14
	v_mul_f32_e32 v19, 0xbfb8aa3b, v15
	v_mul_f32_e32 v22, 0xbfb8aa3b, v16
	v_mul_f32_e32 v23, 0xbfb8aa3b, v17
	v_mul_f32_e32 v24, 0xbfb8aa3b, v10
	v_mul_f32_e32 v25, 0xbfb8aa3b, v11
	v_mul_f32_e32 v26, 0xbfb8aa3b, v12
	v_mul_f32_e32 v27, 0xbfb8aa3b, v13
	v_exp_f32_e32 v18, v18
	v_exp_f32_e32 v19, v19
	v_exp_f32_e32 v22, v22
	v_exp_f32_e32 v23, v23
	v_exp_f32_e32 v24, v24
	v_exp_f32_e32 v25, v25
	v_exp_f32_e32 v26, v26
	v_exp_f32_e32 v27, v27
	v_add_f32_e32 v18, 1.0, v18
	v_add_f32_e32 v19, 1.0, v19
	v_add_f32_e32 v22, 1.0, v22
	v_add_f32_e32 v23, 1.0, v23
	v_add_f32_e32 v24, 1.0, v24
	v_add_f32_e32 v25, 1.0, v25
	v_add_f32_e32 v26, 1.0, v26
	v_add_f32_e32 v27, 1.0, v27
	v_rcp_f32_e32 v18, v18
	v_rcp_f32_e32 v19, v19
	v_rcp_f32_e32 v22, v22
	v_rcp_f32_e32 v23, v23
	v_rcp_f32_e32 v24, v24
	v_rcp_f32_e32 v25, v25
	v_rcp_f32_e32 v26, v26
	v_rcp_f32_e32 v27, v27
	v_pk_mul_f32 v[14:15], v[14:15], v[18:19]
	v_pk_mul_f32 v[16:17], v[16:17], v[22:23]
	v_pk_mul_f32 v[10:11], v[10:11], v[24:25]
	v_pk_mul_f32 v[12:13], v[12:13], v[26:27]
	v_pk_mul_f32 v[6:7], v[6:7], v[14:15]
	v_pk_mul_f32 v[8:9], v[8:9], v[16:17]
	v_pk_mul_f32 v[10:11], v[2:3], v[10:11]
	v_pk_mul_f32 v[12:13], v[4:5], v[12:13]
	v_cvt_pk_bf16_f32 v2, v6, v7
	v_cvt_pk_bf16_f32 v3, v8, v9
	v_cvt_pk_bf16_f32 v4, v10, v11
	v_cvt_pk_bf16_f32 v5, v12, v13
	v_lshl_add_u64 v[6:7], v[20:21], 0, v[134:135]
	global_store_dwordx4 v[6:7], v[2:5], off sc1
	s_andn2_b64 vcc, exec, s[4:5]
	s_mov_b64 s[4:5], -1
	s_cbranch_vccnz .LBB0_1508
	s_andn2_b64 vcc, exec, s[0:1]
	s_cbranch_vccnz .LBB0_1507
	s_barrier
	s_branch .LBB0_1507
